# W_b/W_out/W_q transposes (needed from phase 4 on) moved out of phase 0 onto the 184 blocks that idle through the last round of phase 1
# speedup vs baseline: 1.0116x; 1.0053x over previous
.Ltr_j0d:
	s_sub_u32 s4, s4, 0x980
	s_cmpk_ge_u32 s4, 0x1700
	s_cbranch_scc1 .Ltr_done
	s_mov_b32 s5, s4

.Ltr_loop:
	s_add_u32 s18, s4, s3
	s_cmpk_lt_u32 s18, 0x1700
	s_cselect_b32 s19, s18, s4
	s_mov_b32 s5, s19

.Ltr_a_end:
	v_mad_u32_u24 v4, v78, s12, v1
	v_mad_u32_u24 v5, v79, s12, v1
	v_mad_u32_u24 v6, v80, s12, v1
	v_mad_u32_u24 v7, v81, s12, v1
	global_load_dwordx4 v[32:35], v4, s[10:11]
	global_load_dwordx4 v[36:39], v5, s[10:11]
	global_load_dwordx4 v[40:43], v6, s[10:11]
	global_load_dwordx4 v[44:47], v7, s[10:11]
	s_waitcnt vmcnt(4)
	ds_write2_b32 v8, v16, v17 offset1:1
	ds_write2_b32 v8, v18, v19 offset0:2 offset1:3
	ds_write2_b32 v9, v20, v21 offset1:1
	ds_write2_b32 v9, v22, v23 offset0:2 offset1:3
	ds_write2_b32 v10, v24, v25 offset1:1
	ds_write2_b32 v10, v26, v27 offset0:2 offset1:3
	ds_write2_b32 v11, v28, v29 offset1:1
	ds_write2_b32 v11, v30, v31 offset0:2 offset1:3
	v_and_b32_e32 v82, s27, v2
	v_xor_b32_e32 v82, s26, v82
	v_lshl_add_u32 v82, v82, 7, v14
	v_add_u32_e32 v83, 0x20000, v82
	s_waitcnt lgkmcnt(0)
	s_barrier
	ds_read2_b32 v[48:49], v12 offset1:65
	ds_read2_b32 v[50:51], v12 offset0:130 offset1:195
	ds_read2_b32 v[52:53], v13 offset1:65
	ds_read2_b32 v[54:55], v13 offset0:130 offset1:195
	ds_read2_b32 v[56:57], v12 offset0:32 offset1:97
	ds_read2_b32 v[58:59], v12 offset0:162 offset1:227
	ds_read2_b32 v[60:61], v13 offset0:32 offset1:97
	ds_read2_b32 v[62:63], v13 offset0:162 offset1:227
	s_waitcnt lgkmcnt(4)
	v_cvt_pk_bf16_f32 v64, v48, v49
	v_cvt_pk_bf16_f32 v65, v50, v51
	v_cvt_pk_bf16_f32 v66, v52, v53
	v_cvt_pk_bf16_f32 v67, v54, v55
	s_waitcnt lgkmcnt(0)
	v_cvt_pk_bf16_f32 v68, v56, v57
	v_cvt_pk_bf16_f32 v69, v58, v59
	v_cvt_pk_bf16_f32 v70, v60, v61
	v_cvt_pk_bf16_f32 v71, v62, v63
	global_store_dwordx4 v82, v[64:67], s[16:17]
	global_store_dwordx4 v83, v[68:71], s[16:17]
	s_mov_b64 s[16:17], s[14:15]
	s_mov_b32 s26, s6
	s_mov_b32 s27, s13
	s_mov_b32 s4, s18
	s_cmpk_lt_u32 s4, 0x1700
	s_cbranch_scc0 .Ltr_drain
	s_add_u32 s18, s4, s3
	s_cmpk_lt_u32 s18, 0x1700
	s_cselect_b32 s19, s18, s4
	s_mov_b32 s5, s19

.Ltr_b_end:
	v_mad_u32_u24 v4, v78, s12, v1
	v_mad_u32_u24 v5, v79, s12, v1
	v_mad_u32_u24 v6, v80, s12, v1
	v_mad_u32_u24 v7, v81, s12, v1
	global_load_dwordx4 v[16:19], v4, s[10:11]
	global_load_dwordx4 v[20:23], v5, s[10:11]
	global_load_dwordx4 v[24:27], v6, s[10:11]
	global_load_dwordx4 v[28:31], v7, s[10:11]
	s_waitcnt vmcnt(4)
	ds_write2_b32 v72, v32, v33 offset1:1
	ds_write2_b32 v72, v34, v35 offset0:2 offset1:3
	ds_write2_b32 v73, v36, v37 offset1:1
	ds_write2_b32 v73, v38, v39 offset0:2 offset1:3
	ds_write2_b32 v74, v40, v41 offset1:1
	ds_write2_b32 v74, v42, v43 offset0:2 offset1:3
	ds_write2_b32 v75, v44, v45 offset1:1
	ds_write2_b32 v75, v46, v47 offset0:2 offset1:3
	v_and_b32_e32 v82, s27, v2
	v_xor_b32_e32 v82, s26, v82
	v_lshl_add_u32 v82, v82, 7, v14
	v_add_u32_e32 v83, 0x20000, v82
	s_waitcnt lgkmcnt(0)
	s_barrier
	ds_read2_b32 v[48:49], v76 offset1:65
	ds_read2_b32 v[50:51], v76 offset0:130 offset1:195
	ds_read2_b32 v[52:53], v77 offset1:65
	ds_read2_b32 v[54:55], v77 offset0:130 offset1:195
	ds_read2_b32 v[56:57], v76 offset0:32 offset1:97
	ds_read2_b32 v[58:59], v76 offset0:162 offset1:227
	ds_read2_b32 v[60:61], v77 offset0:32 offset1:97
	ds_read2_b32 v[62:63], v77 offset0:162 offset1:227
	s_waitcnt lgkmcnt(4)
	v_cvt_pk_bf16_f32 v64, v48, v49
	v_cvt_pk_bf16_f32 v65, v50, v51
	v_cvt_pk_bf16_f32 v66, v52, v53
	v_cvt_pk_bf16_f32 v67, v54, v55
	s_waitcnt lgkmcnt(0)
	v_cvt_pk_bf16_f32 v68, v56, v57
	v_cvt_pk_bf16_f32 v69, v58, v59
	v_cvt_pk_bf16_f32 v70, v60, v61
	v_cvt_pk_bf16_f32 v71, v62, v63
	global_store_dwordx4 v82, v[64:67], s[16:17]
	global_store_dwordx4 v83, v[68:71], s[16:17]
	s_mov_b64 s[16:17], s[14:15]
	s_mov_b32 s26, s6
	s_mov_b32 s27, s13
	s_mov_b32 s4, s18
	s_cmpk_lt_u32 s4, 0x1700
	s_cbranch_scc0 .Ltr_drain
	s_branch .Ltr_loop

.LBB0_136:
	s_cmp_lt_u32 s2, 0x128
	s_cbranch_scc1 .Ltq_done
	s_cmp_ge_u32 s2, 0x1e0
	s_cbranch_scc1 .Ltq_done
	s_load_dwordx2 s[30:31], s[0:1], 0x40
	s_load_dwordx2 s[32:33], s[0:1], 0xb0
	s_load_dwordx2 s[34:35], s[0:1], 0xc8
	s_load_dwordx2 s[36:37], s[0:1], 0xd0
	s_load_dwordx2 s[38:39], s[0:1], 0xe0
	s_movk_i32 s3, 184
	v_lshrrev_b32_e32 v0, 4, v204
	v_and_b32_e32 v1, 15, v204
	v_lshlrev_b32_e32 v1, 4, v1
	v_lshrrev_b32_e32 v2, 3, v204
	v_and_b32_e32 v3, 7, v204
	v_add_u32_e32 v8, 0, v0
	v_mul_u32_u24_e32 v8, 0x104, v8
	v_add3_u32 v8, v8, v1, 32
	v_add_u32_e32 v72, 0x4100, v8
	v_add_u32_e32 v9, 16, v0
	v_mul_u32_u24_e32 v9, 0x104, v9
	v_add3_u32 v9, v9, v1, 32
	v_add_u32_e32 v73, 0x4100, v9
	v_add_u32_e32 v10, 32, v0
	v_mul_u32_u24_e32 v10, 0x104, v10
	v_add3_u32 v10, v10, v1, 32
	v_add_u32_e32 v74, 0x4100, v10
	v_add_u32_e32 v11, 48, v0
	v_mul_u32_u24_e32 v11, 0x104, v11
	v_add3_u32 v11, v11, v1, 32
	v_add_u32_e32 v75, 0x4100, v11
	v_mul_u32_u24_e32 v12, 0x820, v3
	v_lshl_add_u32 v12, v2, 2, v12
	v_add_u32_e32 v12, 32, v12
	v_add_u32_e32 v13, 0x410, v12
	v_add_u32_e32 v76, 0x4100, v12
	v_add_u32_e32 v77, 0x4100, v13
	v_lshlrev_b32_e32 v14, 12, v2
	v_lshl_add_u32 v14, v3, 4, v14
	v_add_u32_e32 v78, 0, v0
	v_add_u32_e32 v79, 16, v0
	v_add_u32_e32 v80, 32, v0
	v_add_u32_e32 v81, 48, v0
	s_waitcnt lgkmcnt(0)
	s_sub_u32 s4, s2, 0x128
	s_add_u32 s4, s4, 0x1700
	s_cmpk_ge_u32 s4, 0x2300
	s_cbranch_scc1 .Ltq_done
	s_mov_b32 s5, s4

.Ltq_done:
	s_load_dword s3, s[0:1], 0x120
	s_add_u32 s4, s0, 0x120
	s_addc_u32 s5, s1, 0
	s_waitcnt lgkmcnt(0)
	s_load_dwordx4 s[28:31], s[0:1], 0x110
	v_readlane_b32 s8, v244, 1
	v_readlane_b32 s9, v244, 2
	s_waitcnt lgkmcnt(0)
	s_cmp_lt_i32 s29, 3
	s_cselect_b64 s[6:7], -1, 0
	s_xor_b64 s[8:9], s[8:9], -1
	s_or_b64 s[6:7], s[6:7], s[8:9]
	s_and_b64 vcc, exec, s[6:7]
	s_cbranch_vccnz .LBB0_181
	s_waitcnt vmcnt(0)
	s_waitcnt vmcnt(63) expcnt(7) lgkmcnt(15)
	s_barrier
	s_and_saveexec_b64 s[6:7], s[56:57]
	s_cbranch_execz .LBB0_180
	v_readlane_b32 s8, v244, 0
	s_waitcnt vmcnt(0) expcnt(0) lgkmcnt(0)
	s_nop 0
	v_mov_b32_e32 v0, s8
	ds_read_b32 v2, v0
	ds_read_b32 v0, v0 offset:4
	s_waitcnt lgkmcnt(1)
	v_cmp_ne_u32_e32 vcc, 0, v2
	s_cbranch_vccnz .LBB0_151
	s_load_dwordx2 s[10:11], s[4:5], 0x4
	s_add_u32 s4, s58, 0x1000
	s_addc_u32 s5, s59, 0
	s_add_u32 s8, s58, 0x1100
	s_addc_u32 s9, s59, 0
	s_waitcnt lgkmcnt(0)
	s_mul_i32 s3, s10, s3
	s_add_u32 s10, s58, 0x1200
	s_mul_i32 s3, s3, s11
	s_addc_u32 s11, s59, 0
	s_add_u32 s12, s58, 0x1300
	s_addc_u32 s13, s59, 0
	s_mov_b32 s16, 1
	v_mov_b32_e32 v16, 0
	s_branch .LBB0_141
